# lnstats loads batched 32 in flight (were 128 serialized round trips); attention prologue batched + early tile DMA
# speedup vs baseline: 1.0879x; 1.0310x over previous
.LBB0_218:
	v_ashrrev_i32_e32 v5, 31, v4
	v_mov_b32_e32 v8, 0
	v_lshl_add_u64 v[6:7], v[4:5], 1, v[2:3]
	s_mov_b64 s[6:7], 0
	v_mov_b32_e32 v9, v8
	s_add_u32 s10, s94, 0x2916c000
	s_addc_u32 s11, s95, 0
	v_subrev_u32_e32 v16, s94, v2
	v_lshl_add_u32 v17, v4, 1, v16
	s_mov_b32 s12, 0
.Lln_batch:
	global_load_ushort v20, v17, s[10:11]
	s_add_u32 s10, s10, 0x9000
	s_addc_u32 s11, s11, 0
	global_load_ushort v21, v17, s[10:11]
	s_add_u32 s10, s10, 0x9000
	s_addc_u32 s11, s11, 0
	global_load_ushort v22, v17, s[10:11]
	s_add_u32 s10, s10, 0x9000
	s_addc_u32 s11, s11, 0
	global_load_ushort v23, v17, s[10:11]
	s_add_u32 s10, s10, 0x9000
	s_addc_u32 s11, s11, 0
	global_load_ushort v24, v17, s[10:11]
	s_add_u32 s10, s10, 0x9000
	s_addc_u32 s11, s11, 0
	global_load_ushort v25, v17, s[10:11]
	s_add_u32 s10, s10, 0x9000
	s_addc_u32 s11, s11, 0
	global_load_ushort v26, v17, s[10:11]
	s_add_u32 s10, s10, 0x9000
	s_addc_u32 s11, s11, 0
	global_load_ushort v27, v17, s[10:11]
	s_add_u32 s10, s10, 0x9000
	s_addc_u32 s11, s11, 0
	global_load_ushort v28, v17, s[10:11]
	s_add_u32 s10, s10, 0x9000
	s_addc_u32 s11, s11, 0
	global_load_ushort v29, v17, s[10:11]
	s_add_u32 s10, s10, 0x9000
	s_addc_u32 s11, s11, 0
	global_load_ushort v30, v17, s[10:11]
	s_add_u32 s10, s10, 0x9000
	s_addc_u32 s11, s11, 0
	global_load_ushort v31, v17, s[10:11]
	s_add_u32 s10, s10, 0x9000
	s_addc_u32 s11, s11, 0
	global_load_ushort v32, v17, s[10:11]
	s_add_u32 s10, s10, 0x9000
	s_addc_u32 s11, s11, 0
	global_load_ushort v33, v17, s[10:11]
	s_add_u32 s10, s10, 0x9000
	s_addc_u32 s11, s11, 0
	global_load_ushort v34, v17, s[10:11]
	s_add_u32 s10, s10, 0x9000
	s_addc_u32 s11, s11, 0
	global_load_ushort v35, v17, s[10:11]
	s_add_u32 s10, s10, 0x9000
	s_addc_u32 s11, s11, 0
	global_load_ushort v36, v17, s[10:11]
	s_add_u32 s10, s10, 0x9000
	s_addc_u32 s11, s11, 0
	global_load_ushort v37, v17, s[10:11]
	s_add_u32 s10, s10, 0x9000
	s_addc_u32 s11, s11, 0
	global_load_ushort v38, v17, s[10:11]
	s_add_u32 s10, s10, 0x9000
	s_addc_u32 s11, s11, 0
	global_load_ushort v39, v17, s[10:11]
	s_add_u32 s10, s10, 0x9000
	s_addc_u32 s11, s11, 0
	global_load_ushort v40, v17, s[10:11]
	s_add_u32 s10, s10, 0x9000
	s_addc_u32 s11, s11, 0
	global_load_ushort v41, v17, s[10:11]
	s_add_u32 s10, s10, 0x9000
	s_addc_u32 s11, s11, 0
	global_load_ushort v42, v17, s[10:11]
	s_add_u32 s10, s10, 0x9000
	s_addc_u32 s11, s11, 0
	global_load_ushort v43, v17, s[10:11]
	s_add_u32 s10, s10, 0x9000
	s_addc_u32 s11, s11, 0
	global_load_ushort v44, v17, s[10:11]
	s_add_u32 s10, s10, 0x9000
	s_addc_u32 s11, s11, 0
	global_load_ushort v45, v17, s[10:11]
	s_add_u32 s10, s10, 0x9000
	s_addc_u32 s11, s11, 0
	global_load_ushort v46, v17, s[10:11]
	s_add_u32 s10, s10, 0x9000
	s_addc_u32 s11, s11, 0
	global_load_ushort v47, v17, s[10:11]
	s_add_u32 s10, s10, 0x9000
	s_addc_u32 s11, s11, 0
	global_load_ushort v48, v17, s[10:11]
	s_add_u32 s10, s10, 0x9000
	s_addc_u32 s11, s11, 0
	global_load_ushort v49, v17, s[10:11]
	s_add_u32 s10, s10, 0x9000
	s_addc_u32 s11, s11, 0
	global_load_ushort v50, v17, s[10:11]
	s_add_u32 s10, s10, 0x9000
	s_addc_u32 s11, s11, 0
	global_load_ushort v51, v17, s[10:11]
	s_add_u32 s10, s10, 0x9000
	s_addc_u32 s11, s11, 0
	s_add_i32 s12, s12, 1
	s_waitcnt vmcnt(31)
	v_lshlrev_b32_e32 v14, 16, v20
	v_mul_f32_e32 v15, v14, v14
	v_pk_add_f32 v[8:9], v[8:9], v[14:15]
	s_waitcnt vmcnt(30)
	v_lshlrev_b32_e32 v14, 16, v21
	v_mul_f32_e32 v15, v14, v14
	v_pk_add_f32 v[8:9], v[8:9], v[14:15]
	s_waitcnt vmcnt(29)
	v_lshlrev_b32_e32 v14, 16, v22
	v_mul_f32_e32 v15, v14, v14
	v_pk_add_f32 v[8:9], v[8:9], v[14:15]
	s_waitcnt vmcnt(28)
	v_lshlrev_b32_e32 v14, 16, v23
	v_mul_f32_e32 v15, v14, v14
	v_pk_add_f32 v[8:9], v[8:9], v[14:15]
	s_waitcnt vmcnt(27)
	v_lshlrev_b32_e32 v14, 16, v24
	v_mul_f32_e32 v15, v14, v14
	v_pk_add_f32 v[8:9], v[8:9], v[14:15]
	s_waitcnt vmcnt(26)
	v_lshlrev_b32_e32 v14, 16, v25
	v_mul_f32_e32 v15, v14, v14
	v_pk_add_f32 v[8:9], v[8:9], v[14:15]
	s_waitcnt vmcnt(25)
	v_lshlrev_b32_e32 v14, 16, v26
	v_mul_f32_e32 v15, v14, v14
	v_pk_add_f32 v[8:9], v[8:9], v[14:15]
	s_waitcnt vmcnt(24)
	v_lshlrev_b32_e32 v14, 16, v27
	v_mul_f32_e32 v15, v14, v14
	v_pk_add_f32 v[8:9], v[8:9], v[14:15]
	s_waitcnt vmcnt(23)
	v_lshlrev_b32_e32 v14, 16, v28
	v_mul_f32_e32 v15, v14, v14
	v_pk_add_f32 v[8:9], v[8:9], v[14:15]
	s_waitcnt vmcnt(22)
	v_lshlrev_b32_e32 v14, 16, v29
	v_mul_f32_e32 v15, v14, v14
	v_pk_add_f32 v[8:9], v[8:9], v[14:15]
	s_waitcnt vmcnt(21)
	v_lshlrev_b32_e32 v14, 16, v30
	v_mul_f32_e32 v15, v14, v14
	v_pk_add_f32 v[8:9], v[8:9], v[14:15]
	s_waitcnt vmcnt(20)
	v_lshlrev_b32_e32 v14, 16, v31
	v_mul_f32_e32 v15, v14, v14
	v_pk_add_f32 v[8:9], v[8:9], v[14:15]
	s_waitcnt vmcnt(19)
	v_lshlrev_b32_e32 v14, 16, v32
	v_mul_f32_e32 v15, v14, v14
	v_pk_add_f32 v[8:9], v[8:9], v[14:15]
	s_waitcnt vmcnt(18)
	v_lshlrev_b32_e32 v14, 16, v33
	v_mul_f32_e32 v15, v14, v14
	v_pk_add_f32 v[8:9], v[8:9], v[14:15]
	s_waitcnt vmcnt(17)
	v_lshlrev_b32_e32 v14, 16, v34
	v_mul_f32_e32 v15, v14, v14
	v_pk_add_f32 v[8:9], v[8:9], v[14:15]
	s_waitcnt vmcnt(16)
	v_lshlrev_b32_e32 v14, 16, v35
	v_mul_f32_e32 v15, v14, v14
	v_pk_add_f32 v[8:9], v[8:9], v[14:15]
	s_waitcnt vmcnt(15)
	v_lshlrev_b32_e32 v14, 16, v36
	v_mul_f32_e32 v15, v14, v14
	v_pk_add_f32 v[8:9], v[8:9], v[14:15]
	s_waitcnt vmcnt(14)
	v_lshlrev_b32_e32 v14, 16, v37
	v_mul_f32_e32 v15, v14, v14
	v_pk_add_f32 v[8:9], v[8:9], v[14:15]
	s_waitcnt vmcnt(13)
	v_lshlrev_b32_e32 v14, 16, v38
	v_mul_f32_e32 v15, v14, v14
	v_pk_add_f32 v[8:9], v[8:9], v[14:15]
	s_waitcnt vmcnt(12)
	v_lshlrev_b32_e32 v14, 16, v39
	v_mul_f32_e32 v15, v14, v14
	v_pk_add_f32 v[8:9], v[8:9], v[14:15]
	s_waitcnt vmcnt(11)
	v_lshlrev_b32_e32 v14, 16, v40
	v_mul_f32_e32 v15, v14, v14
	v_pk_add_f32 v[8:9], v[8:9], v[14:15]
	s_waitcnt vmcnt(10)
	v_lshlrev_b32_e32 v14, 16, v41
	v_mul_f32_e32 v15, v14, v14
	v_pk_add_f32 v[8:9], v[8:9], v[14:15]
	s_waitcnt vmcnt(9)
	v_lshlrev_b32_e32 v14, 16, v42
	v_mul_f32_e32 v15, v14, v14
	v_pk_add_f32 v[8:9], v[8:9], v[14:15]
	s_waitcnt vmcnt(8)
	v_lshlrev_b32_e32 v14, 16, v43
	v_mul_f32_e32 v15, v14, v14
	v_pk_add_f32 v[8:9], v[8:9], v[14:15]
	s_waitcnt vmcnt(7)
	v_lshlrev_b32_e32 v14, 16, v44
	v_mul_f32_e32 v15, v14, v14
	v_pk_add_f32 v[8:9], v[8:9], v[14:15]
	s_waitcnt vmcnt(6)
	v_lshlrev_b32_e32 v14, 16, v45
	v_mul_f32_e32 v15, v14, v14
	v_pk_add_f32 v[8:9], v[8:9], v[14:15]
	s_waitcnt vmcnt(5)
	v_lshlrev_b32_e32 v14, 16, v46
	v_mul_f32_e32 v15, v14, v14
	v_pk_add_f32 v[8:9], v[8:9], v[14:15]
	s_waitcnt vmcnt(4)
	v_lshlrev_b32_e32 v14, 16, v47
	v_mul_f32_e32 v15, v14, v14
	v_pk_add_f32 v[8:9], v[8:9], v[14:15]
	s_waitcnt vmcnt(3)
	v_lshlrev_b32_e32 v14, 16, v48
	v_mul_f32_e32 v15, v14, v14
	v_pk_add_f32 v[8:9], v[8:9], v[14:15]
	s_waitcnt vmcnt(2)
	v_lshlrev_b32_e32 v14, 16, v49
	v_mul_f32_e32 v15, v14, v14
	v_pk_add_f32 v[8:9], v[8:9], v[14:15]
	s_waitcnt vmcnt(1)
	v_lshlrev_b32_e32 v14, 16, v50
	v_mul_f32_e32 v15, v14, v14
	v_pk_add_f32 v[8:9], v[8:9], v[14:15]
	s_waitcnt vmcnt(0)
	v_lshlrev_b32_e32 v14, 16, v51
	v_mul_f32_e32 v15, v14, v14
	v_pk_add_f32 v[8:9], v[8:9], v[14:15]
	s_cmp_eq_u32 s12, 4
	s_cbranch_scc0 .Lln_batch
	ds_write_b64 v11, v[8:9]
	s_waitcnt lgkmcnt(0)
	s_barrier
	s_and_saveexec_b64 s[6:7], s[0:1]
	s_cbranch_execz .LBB0_217
	ds_read2st64_b64 v[6:9], v11 offset1:1
	s_mov_b32 s8, 0x3a800000
	s_waitcnt lgkmcnt(0)
	v_pk_add_f32 v[6:7], v[6:7], 0 op_sel_hi:[1,0]
	s_nop 0
	v_pk_add_f32 v[12:13], v[6:7], v[8:9]
	ds_read2st64_b64 v[6:9], v11 offset0:2 offset1:3
	s_waitcnt lgkmcnt(0)
	v_pk_add_f32 v[6:7], v[12:13], v[6:7]
	s_nop 0
	v_pk_add_f32 v[12:13], v[6:7], v[8:9]
	ds_read2st64_b64 v[6:9], v11 offset0:4 offset1:5
	s_waitcnt lgkmcnt(0)
	v_pk_add_f32 v[6:7], v[12:13], v[6:7]
	s_nop 0
	v_pk_add_f32 v[12:13], v[6:7], v[8:9]
	ds_read2st64_b64 v[6:9], v11 offset0:6 offset1:7
	s_waitcnt lgkmcnt(0)
	v_pk_add_f32 v[6:7], v[12:13], v[6:7]
	s_nop 0
	v_pk_add_f32 v[6:7], v[6:7], v[8:9]
	s_nop 0
	v_pk_mul_f32 v[6:7], v[6:7], s[8:9] op_sel_hi:[1,0]
	s_nop 0
	v_fma_f32 v5, -v6, v6, v7
	v_max_f32_e32 v5, 0, v5
	v_lshlrev_b32_e32 v7, 1, v10
	v_add_f32_e32 v5, 0x358637bd, v5
	v_lshl_or_b32 v8, s5, 7, v7
	v_cmp_gt_f32_e32 vcc, s70, v5
	v_mul_f32_e32 v7, 0x4b800000, v5
	v_ashrrev_i32_e32 v9, 31, v8
	v_cndmask_b32_e32 v5, v5, v7, vcc
	v_rsq_f32_e32 v5, v5
	v_lshl_add_u64 v[8:9], v[8:9], 2, s[2:3]
	v_mul_f32_e32 v7, 0x45800000, v5
	v_cndmask_b32_e32 v7, v5, v7, vcc
	global_store_dwordx2 v[8:9], v[6:7], off
	s_branch .LBB0_217

.LBB0_281:
	s_and_b32 s23, s34, 0xfffffe07
	s_and_b32 s27, s34, 0x38
	s_lshl_b32 s27, s27, 3
	s_or_b32 s23, s23, s27
	s_and_b32 s27, s34, 0x1c0
	s_lshr_b32 s27, s27, 3
	s_or_b32 s23, s23, s27
	s_lshr_b32 s0, s23, 1
	s_and_b32 s6, s0, 30
	s_ashr_i32 s4, s23, 9
	s_lshl_b32 s5, s4, 11
	s_lshl_b32 s1, s6, 6
	s_or_b32 s7, s1, s5
	s_lshl_b32 s1, s23, 4
	s_and_b32 s1, s1, 48
	s_or_b32 s7, s7, s1
	s_bfe_u32 s0, s23, 0x30006
	v_or_b32_e32 v184, s7, v192
	v_mov_b64_e32 v[30:31], s[50:51]
	v_mad_i64_i32 v[186:187], s[8:9], v184, s37, v[30:31]
	s_lshl_b32 s42, s0, 8
	v_or_b32_e32 v180, 64, v184
	v_mad_i64_i32 v[182:183], s[8:9], v180, s37, v[30:31]
	v_sub_u32_e64 v111, s6, 3 clamp
	v_sub_u32_e64 v112, s6, 4 clamp
	v_lshlrev_b32_e32 v194, 1, v170
	v_readfirstlane_b32 s6, v111
	v_readfirstlane_b32 s7, v112
	s_min_u32 s14, s6, 24
	s_min_u32 s15, s7, 24
	s_sub_i32 s59, s14, s15
	s_lshl_b32 s13, s0, 7
	s_add_i32 s2, s59, 8
	v_lshl_add_u64 v[2:3], v[186:187], 0, s[42:43]
	v_lshl_add_u64 v[4:5], v[182:183], 0, s[42:43]
	v_lshl_add_u64 v[2:3], v[2:3], 0, v[194:195]
	v_lshl_add_u64 v[4:5], v[4:5], 0, v[194:195]
	v_lshl_add_u64 v[2:3], v[2:3], 0, s[10:11]
	v_lshl_add_u64 v[4:5], v[4:5], 0, s[10:11]
	s_barrier
	s_bfe_u32 s27, s23, 0x30003
	s_lshl_b32 s27, s27, 2
	s_sub_i32 s42, s27, 4
	s_max_i32 s42, s42, 0
	s_min_i32 s32, s42, 24
	s_sub_i32 s42, s27, 1
	s_max_i32 s42, s42, 0
	s_min_i32 s42, s42, 24
	s_add_i32 s42, s42, 8
	s_sub_i32 s78, s42, s32
	s_mov_b32 s71, 0
	s_mov_b32 s98, 0
	s_mov_b32 s99, 0
	s_bfe_u32 s27, s12, 0x10001
	s_lshl_b32 s27, s27, 3
	v_lshrrev_b32_e32 v242, 1, v197
	v_sub_u32_e32 v243, v192, v242
	v_and_b32_e32 v243, 3, v243
	v_add_u32_e32 v244, v243, v242
	v_add_u32_e32 v244, s27, v244
	v_and_b32_e32 v244, 15, v244
	v_xor_b32_e32 v245, v192, v244
	v_and_b32_e32 v245, 12, v245
	v_or_b32_e32 v243, v243, v245
	v_lshlrev_b32_e32 v243, 4, v243
	v_lshrrev_b32_e32 v246, 2, v197
	s_lshl_b32 s27, s12, 2
	v_add_u32_e32 v246, s27, v246
	v_mul_u32_u24_e32 v246, 0x6800, v246
	v_add_u32_e32 v229, v246, v243
	v_or_b32_e32 v242, v172, v192
	v_lshrrev_b32_e32 v243, 3, v242
	v_and_b32_e32 v244, 6, v243
	v_and_b32_e32 v245, 7, v242
	v_sub_u32_e32 v245, v245, v244
	v_and_b32_e32 v245, 7, v245
	v_lshlrev_b32_e32 v245, 4, v245
	s_lshl_b32 s27, s12, 3
	v_add_u32_e32 v243, s27, v243
	v_mul_u32_u24_e32 v243, 0x9000, v243
	v_add_u32_e32 v254, v243, v245
	s_mov_b32 s9, 0
	s_sub_i32 s27, s9, s78
	s_lshr_b32 s42, s23, 9
	s_lshl_b32 s101, s42, 2
	s_add_i32 s27, s27, s101
	s_add_i32 s27, s27, 0x100
	s_lshl_b32 s42, s42, 5
	s_add_i32 s42, s42, s32
	s_add_i32 s42, s42, s9
	s_cmp_lt_u32 s9, s78
	s_cselect_b32 s27, s42, s27
	s_lshl_b32 s27, s27, 6
	s_mul_i32 s42, s27, s37
	s_add_u32 s10, s50, s42
	s_addc_u32 s11, s51, 0
	s_lshl_b32 s101, s13, 1
	s_add_i32 s101, s101, 0x2800
	s_add_u32 s10, s10, s101
	s_addc_u32 s11, s11, 0
	s_lshl_b32 s8, s12, 10
	s_add_i32 s8, s8, s98
	s_mov_b32 m0, s8
	s_add_i32 s8, s8, 0x2000
	global_load_lds_dwordx4 v229, s[10:11]
	s_mov_b32 m0, s8
	s_add_u32 s10, s10, 0xd0000
	s_addc_u32 s11, s11, 0
	global_load_lds_dwordx4 v229, s[10:11]
	v_readlane_b32 s10, v252, 55
	v_readlane_b32 s11, v252, 56
	s_mul_i32 s42, s13, 0x9000
	s_lshl_b32 s101, s27, 1
	s_add_i32 s42, s42, s101
	s_add_i32 s8, s8, 0x2000
	s_add_u32 s10, s10, s42
	s_addc_u32 s11, s11, 0
	s_mov_b32 m0, s8
	s_add_i32 s8, s8, 0x2000
	global_load_lds_dwordx4 v254, s[10:11]
	s_mov_b32 m0, s8
	s_add_u32 s10, s10, 0x240000
	s_addc_u32 s11, s11, 0
	global_load_lds_dwordx4 v254, s[10:11]
	s_add_i32 s98, s98, 0x8000
	s_cmp_eq_u32 s98, 0x18000
	s_cselect_b32 s98, 0, s98
	s_mov_b32 s9, 1
	s_sub_i32 s27, s9, s78
	s_lshr_b32 s42, s23, 9
	s_lshl_b32 s101, s42, 2
	s_add_i32 s27, s27, s101
	s_add_i32 s27, s27, 0x100
	s_lshl_b32 s42, s42, 5
	s_add_i32 s42, s42, s32
	s_add_i32 s42, s42, s9
	s_cmp_lt_u32 s9, s78
	s_cselect_b32 s27, s42, s27
	s_lshl_b32 s27, s27, 6
	s_mul_i32 s42, s27, s37
	s_add_u32 s10, s50, s42
	s_addc_u32 s11, s51, 0
	s_lshl_b32 s101, s13, 1
	s_add_i32 s101, s101, 0x2800
	s_add_u32 s10, s10, s101
	s_addc_u32 s11, s11, 0
	s_lshl_b32 s8, s12, 10
	s_add_i32 s8, s8, s98
	s_mov_b32 m0, s8
	s_add_i32 s8, s8, 0x2000
	global_load_lds_dwordx4 v229, s[10:11]
	s_mov_b32 m0, s8
	s_add_u32 s10, s10, 0xd0000
	s_addc_u32 s11, s11, 0
	global_load_lds_dwordx4 v229, s[10:11]
	v_readlane_b32 s10, v252, 55
	v_readlane_b32 s11, v252, 56
	s_mul_i32 s42, s13, 0x9000
	s_lshl_b32 s101, s27, 1
	s_add_i32 s42, s42, s101
	s_add_i32 s8, s8, 0x2000
	s_add_u32 s10, s10, s42
	s_addc_u32 s11, s11, 0
	s_mov_b32 m0, s8
	s_add_i32 s8, s8, 0x2000
	global_load_lds_dwordx4 v254, s[10:11]
	s_mov_b32 m0, s8
	s_add_u32 s10, s10, 0x240000
	s_addc_u32 s11, s11, 0
	global_load_lds_dwordx4 v254, s[10:11]
	s_add_i32 s98, s98, 0x8000
	s_cmp_eq_u32 s98, 0x18000
	s_cselect_b32 s98, 0, s98
	s_and_b32 s27, s23, 3
	s_lshl_b32 s27, s27, 4
	s_sub_i32 s27, s27, 8
	s_max_i32 s27, s27, 0
	s_min_i32 s42, s27, 32
	s_lshr_b32 s101, s42, 3
	v_lshrrev_b32_e32 v242, 2, v192
	v_and_b32_e32 v243, 3, v192
	v_lshl_add_u32 v244, v242, 3, v243
	v_add_u32_e32 v245, s42, v244
	v_add_u32_e32 v246, s101, v242
	v_and_b32_e32 v246, 1, v246
	v_lshl_or_b32 v246, v246, 2, v243
	v_lshrrev_b32_e32 v247, 2, v197
	v_lshl_add_u32 v246, v246, 1, v247
	v_and_b32_e32 v246, 15, v246
	v_lshlrev_b32_e32 v246, 4, v246
	v_lshl_add_u32 v255, v245, 8, v246
	v_and_b32_e32 v246, 1, v242
	v_lshl_or_b32 v246, v246, 2, v243
	v_lshl_add_u32 v246, v246, 1, v247
	v_and_b32_e32 v246, 15, v246
	v_lshlrev_b32_e32 v246, 4, v246
	v_lshl_add_u32 v190, v244, 8, v246
	v_and_b32_e32 v242, 14, v192
	v_add_u32_e32 v242, v242, v247
	v_lshlrev_b32_e32 v243, 7, v192
	v_add_u32_e32 v243, 0x4000, v243
	v_add_u32_e32 v244, s101, v242
	v_and_b32_e32 v244, 7, v244
	v_lshl_add_u32 v191, v244, 4, v243
	v_and_b32_e32 v244, 7, v242
	v_lshl_add_u32 v181, v244, 4, v243
	v_add_u32_e32 v244, 4, v242
	v_and_b32_e32 v244, 7, v244
	v_lshl_add_u32 v249, v244, 4, v243
	global_load_dwordx4 v[146:149], v[2:3], off
	global_load_dwordx4 v[150:153], v[2:3], off offset:64
	global_load_dwordx4 v[154:157], v[2:3], off offset:128
	global_load_dwordx4 v[158:161], v[2:3], off offset:192
	global_load_dwordx4 v[98:101], v[4:5], off
	global_load_dwordx4 v[102:105], v[4:5], off offset:64
	global_load_dwordx4 v[106:109], v[4:5], off offset:128
	global_load_dwordx4 v[110:113], v[4:5], off offset:192
	global_load_dwordx4 v[114:117], v[176:177], off
	global_load_dwordx4 v[118:121], v[176:177], off offset:16
	global_load_dwordx4 v[122:125], v[176:177], off offset:128
	global_load_dwordx4 v[126:129], v[176:177], off offset:144
	global_load_dwordx4 v[130:133], v[176:177], off offset:256
	global_load_dwordx4 v[134:137], v[176:177], off offset:272
	global_load_dwordx4 v[138:141], v[176:177], off offset:384
	global_load_dwordx4 v[142:145], v[176:177], off offset:400
	s_waitcnt vmcnt(8)
	v_lshlrev_b32_e32 v8, 16, v146
	v_lshlrev_b32_e32 v9, 16, v98
	v_and_b32_e32 v10, 0xffff0000, v146
	v_and_b32_e32 v11, 0xffff0000, v98
	v_mul_f32_e32 v6, v8, v8
	v_mul_f32_e32 v7, v9, v9
	v_fmac_f32_e32 v6, v10, v10
	v_fmac_f32_e32 v7, v11, v11
	v_lshlrev_b32_e32 v8, 16, v147
	v_lshlrev_b32_e32 v9, 16, v99
	v_and_b32_e32 v10, 0xffff0000, v147
	v_and_b32_e32 v11, 0xffff0000, v99
	v_fmac_f32_e32 v6, v8, v8
	v_fmac_f32_e32 v7, v9, v9
	v_fmac_f32_e32 v6, v10, v10
	v_fmac_f32_e32 v7, v11, v11
	v_lshlrev_b32_e32 v8, 16, v148
	v_lshlrev_b32_e32 v9, 16, v100
	v_and_b32_e32 v10, 0xffff0000, v148
	v_and_b32_e32 v11, 0xffff0000, v100
	v_fmac_f32_e32 v6, v8, v8
	v_fmac_f32_e32 v7, v9, v9
	v_fmac_f32_e32 v6, v10, v10
	v_fmac_f32_e32 v7, v11, v11
	v_lshlrev_b32_e32 v8, 16, v149
	v_lshlrev_b32_e32 v9, 16, v101
	v_and_b32_e32 v10, 0xffff0000, v149
	v_and_b32_e32 v11, 0xffff0000, v101
	v_fmac_f32_e32 v6, v8, v8
	v_fmac_f32_e32 v7, v9, v9
	v_fmac_f32_e32 v6, v10, v10
	v_fmac_f32_e32 v7, v11, v11
	v_lshlrev_b32_e32 v8, 16, v150
	v_lshlrev_b32_e32 v9, 16, v102
	v_and_b32_e32 v10, 0xffff0000, v150
	v_and_b32_e32 v11, 0xffff0000, v102
	v_fmac_f32_e32 v6, v8, v8
	v_fmac_f32_e32 v7, v9, v9
	v_fmac_f32_e32 v6, v10, v10
	v_fmac_f32_e32 v7, v11, v11
	v_lshlrev_b32_e32 v8, 16, v151
	v_lshlrev_b32_e32 v9, 16, v103
	v_and_b32_e32 v10, 0xffff0000, v151
	v_and_b32_e32 v11, 0xffff0000, v103
	v_fmac_f32_e32 v6, v8, v8
	v_fmac_f32_e32 v7, v9, v9
	v_fmac_f32_e32 v6, v10, v10
	v_fmac_f32_e32 v7, v11, v11
	v_lshlrev_b32_e32 v8, 16, v152
	v_lshlrev_b32_e32 v9, 16, v104
	v_and_b32_e32 v10, 0xffff0000, v152
	v_and_b32_e32 v11, 0xffff0000, v104
	v_fmac_f32_e32 v6, v8, v8
	v_fmac_f32_e32 v7, v9, v9
	v_fmac_f32_e32 v6, v10, v10
	v_fmac_f32_e32 v7, v11, v11
	v_lshlrev_b32_e32 v8, 16, v153
	v_lshlrev_b32_e32 v9, 16, v105
	v_and_b32_e32 v10, 0xffff0000, v153
	v_and_b32_e32 v11, 0xffff0000, v105
	v_fmac_f32_e32 v6, v8, v8
	v_fmac_f32_e32 v7, v9, v9
	v_fmac_f32_e32 v6, v10, v10
	v_fmac_f32_e32 v7, v11, v11
	v_lshlrev_b32_e32 v8, 16, v154
	v_lshlrev_b32_e32 v9, 16, v106
	v_and_b32_e32 v10, 0xffff0000, v154
	v_and_b32_e32 v11, 0xffff0000, v106
	v_fmac_f32_e32 v6, v8, v8
	v_fmac_f32_e32 v7, v9, v9
	v_fmac_f32_e32 v6, v10, v10
	v_fmac_f32_e32 v7, v11, v11
	v_lshlrev_b32_e32 v8, 16, v155
	v_lshlrev_b32_e32 v9, 16, v107
	v_and_b32_e32 v10, 0xffff0000, v155
	v_and_b32_e32 v11, 0xffff0000, v107
	v_fmac_f32_e32 v6, v8, v8
	v_fmac_f32_e32 v7, v9, v9
	v_fmac_f32_e32 v6, v10, v10
	v_fmac_f32_e32 v7, v11, v11
	v_lshlrev_b32_e32 v8, 16, v156
	v_lshlrev_b32_e32 v9, 16, v108
	v_and_b32_e32 v10, 0xffff0000, v156
	v_and_b32_e32 v11, 0xffff0000, v108
	v_fmac_f32_e32 v6, v8, v8
	v_fmac_f32_e32 v7, v9, v9
	v_fmac_f32_e32 v6, v10, v10
	v_fmac_f32_e32 v7, v11, v11
	v_lshlrev_b32_e32 v8, 16, v157
	v_lshlrev_b32_e32 v9, 16, v109
	v_and_b32_e32 v10, 0xffff0000, v157
	v_and_b32_e32 v11, 0xffff0000, v109
	v_fmac_f32_e32 v6, v8, v8
	v_fmac_f32_e32 v7, v9, v9
	v_fmac_f32_e32 v6, v10, v10
	v_fmac_f32_e32 v7, v11, v11
	v_lshlrev_b32_e32 v8, 16, v158
	v_lshlrev_b32_e32 v9, 16, v110
	v_and_b32_e32 v10, 0xffff0000, v158
	v_and_b32_e32 v11, 0xffff0000, v110
	v_fmac_f32_e32 v6, v8, v8
	v_fmac_f32_e32 v7, v9, v9
	v_fmac_f32_e32 v6, v10, v10
	v_fmac_f32_e32 v7, v11, v11
	v_lshlrev_b32_e32 v8, 16, v159
	v_lshlrev_b32_e32 v9, 16, v111
	v_and_b32_e32 v10, 0xffff0000, v159
	v_and_b32_e32 v11, 0xffff0000, v111
	v_fmac_f32_e32 v6, v8, v8
	v_fmac_f32_e32 v7, v9, v9
	v_fmac_f32_e32 v6, v10, v10
	v_fmac_f32_e32 v7, v11, v11
	v_lshlrev_b32_e32 v8, 16, v160
	v_lshlrev_b32_e32 v9, 16, v112
	v_and_b32_e32 v10, 0xffff0000, v160
	v_and_b32_e32 v11, 0xffff0000, v112
	v_fmac_f32_e32 v6, v8, v8
	v_fmac_f32_e32 v7, v9, v9
	v_fmac_f32_e32 v6, v10, v10
	v_fmac_f32_e32 v7, v11, v11
	v_lshlrev_b32_e32 v8, 16, v161
	v_lshlrev_b32_e32 v9, 16, v113
	v_and_b32_e32 v10, 0xffff0000, v161
	v_and_b32_e32 v11, 0xffff0000, v113
	v_fmac_f32_e32 v6, v8, v8
	v_fmac_f32_e32 v7, v9, v9
	v_fmac_f32_e32 v6, v10, v10
	v_fmac_f32_e32 v7, v11, v11
	ds_bpermute_b32 v8, v171, v6
	ds_bpermute_b32 v9, v171, v7
	s_waitcnt lgkmcnt(0)
	v_add_f32_e32 v6, v6, v8
	v_add_f32_e32 v7, v7, v9
	ds_bpermute_b32 v8, v199, v6
	ds_bpermute_b32 v9, v199, v7
	s_waitcnt lgkmcnt(0)
	v_add_f32_e32 v6, v6, v8
	v_add_f32_e32 v7, v7, v9
	v_fmamk_f32 v6, v6, 0x3c000000, v230
	v_mul_f32_e32 v8, 0x4b800000, v6
	v_cmp_gt_f32_e32 vcc, s70, v6
	s_nop 1
	v_cndmask_b32_e32 v6, v6, v8, vcc
	v_rsq_f32_e32 v14, v6
	s_nop 0
	v_mul_f32_e32 v8, 0x45800000, v14
	v_cndmask_b32_e32 v14, v14, v8, vcc
	v_mul_f32_e32 v14, 0x3db504f3, v14
	v_fmamk_f32 v7, v7, 0x3c000000, v230
	v_mul_f32_e32 v9, 0x4b800000, v7
	v_cmp_gt_f32_e32 vcc, s70, v7
	s_nop 1
	v_cndmask_b32_e32 v7, v7, v9, vcc
	v_rsq_f32_e32 v15, v7
	s_nop 0
	v_mul_f32_e32 v9, 0x45800000, v15
	v_cndmask_b32_e32 v15, v15, v9, vcc
	v_mul_f32_e32 v15, 0x3db504f3, v15
	s_waitcnt vmcnt(0)
	v_lshlrev_b32_e32 v16, 16, v146
	v_and_b32_e32 v17, 0xffff0000, v146
	v_mul_f32_e32 v16, v14, v16
	v_mul_f32_e32 v17, v14, v17
	v_mul_f32_e32 v16, v114, v16
	v_mul_f32_e32 v17, v115, v17
	v_cvt_pk_bf16_f32 v50, v16, v17
	v_lshlrev_b32_e32 v16, 16, v147
	v_and_b32_e32 v17, 0xffff0000, v147
	v_mul_f32_e32 v16, v14, v16
	v_mul_f32_e32 v17, v14, v17
	v_mul_f32_e32 v16, v116, v16
	v_mul_f32_e32 v17, v117, v17
	v_cvt_pk_bf16_f32 v51, v16, v17
	v_lshlrev_b32_e32 v16, 16, v148
	v_and_b32_e32 v17, 0xffff0000, v148
	v_mul_f32_e32 v16, v14, v16
	v_mul_f32_e32 v17, v14, v17
	v_mul_f32_e32 v16, v118, v16
	v_mul_f32_e32 v17, v119, v17
	v_cvt_pk_bf16_f32 v52, v16, v17
	v_lshlrev_b32_e32 v16, 16, v149
	v_and_b32_e32 v17, 0xffff0000, v149
	v_mul_f32_e32 v16, v14, v16
	v_mul_f32_e32 v17, v14, v17
	v_mul_f32_e32 v16, v120, v16
	v_mul_f32_e32 v17, v121, v17
	v_cvt_pk_bf16_f32 v53, v16, v17
	v_lshlrev_b32_e32 v16, 16, v98
	v_and_b32_e32 v17, 0xffff0000, v98
	v_mul_f32_e32 v16, v15, v16
	v_mul_f32_e32 v17, v15, v17
	v_mul_f32_e32 v16, v114, v16
	v_mul_f32_e32 v17, v115, v17
	v_cvt_pk_bf16_f32 v78, v16, v17
	v_lshlrev_b32_e32 v16, 16, v99
	v_and_b32_e32 v17, 0xffff0000, v99
	v_mul_f32_e32 v16, v15, v16
	v_mul_f32_e32 v17, v15, v17
	v_mul_f32_e32 v16, v116, v16
	v_mul_f32_e32 v17, v117, v17
	v_cvt_pk_bf16_f32 v79, v16, v17
	v_lshlrev_b32_e32 v16, 16, v100
	v_and_b32_e32 v17, 0xffff0000, v100
	v_mul_f32_e32 v16, v15, v16
	v_mul_f32_e32 v17, v15, v17
	v_mul_f32_e32 v16, v118, v16
	v_mul_f32_e32 v17, v119, v17
	v_cvt_pk_bf16_f32 v80, v16, v17
	v_lshlrev_b32_e32 v16, 16, v101
	v_and_b32_e32 v17, 0xffff0000, v101
	v_mul_f32_e32 v16, v15, v16
	v_mul_f32_e32 v17, v15, v17
	v_mul_f32_e32 v16, v120, v16
	v_mul_f32_e32 v17, v121, v17
	v_cvt_pk_bf16_f32 v81, v16, v17
	v_lshlrev_b32_e32 v16, 16, v150
	v_and_b32_e32 v17, 0xffff0000, v150
	v_mul_f32_e32 v16, v14, v16
	v_mul_f32_e32 v17, v14, v17
	v_mul_f32_e32 v16, v122, v16
	v_mul_f32_e32 v17, v123, v17
	v_cvt_pk_bf16_f32 v54, v16, v17
	v_lshlrev_b32_e32 v16, 16, v151
	v_and_b32_e32 v17, 0xffff0000, v151
	v_mul_f32_e32 v16, v14, v16
	v_mul_f32_e32 v17, v14, v17
	v_mul_f32_e32 v16, v124, v16
	v_mul_f32_e32 v17, v125, v17
	v_cvt_pk_bf16_f32 v55, v16, v17
	v_lshlrev_b32_e32 v16, 16, v152
	v_and_b32_e32 v17, 0xffff0000, v152
	v_mul_f32_e32 v16, v14, v16
	v_mul_f32_e32 v17, v14, v17
	v_mul_f32_e32 v16, v126, v16
	v_mul_f32_e32 v17, v127, v17
	v_cvt_pk_bf16_f32 v56, v16, v17
	v_lshlrev_b32_e32 v16, 16, v153
	v_and_b32_e32 v17, 0xffff0000, v153
	v_mul_f32_e32 v16, v14, v16
	v_mul_f32_e32 v17, v14, v17
	v_mul_f32_e32 v16, v128, v16
	v_mul_f32_e32 v17, v129, v17
	v_cvt_pk_bf16_f32 v57, v16, v17
	v_lshlrev_b32_e32 v16, 16, v102
	v_and_b32_e32 v17, 0xffff0000, v102
	v_mul_f32_e32 v16, v15, v16
	v_mul_f32_e32 v17, v15, v17
	v_mul_f32_e32 v16, v122, v16
	v_mul_f32_e32 v17, v123, v17
	v_cvt_pk_bf16_f32 v82, v16, v17
	v_lshlrev_b32_e32 v16, 16, v103
	v_and_b32_e32 v17, 0xffff0000, v103
	v_mul_f32_e32 v16, v15, v16
	v_mul_f32_e32 v17, v15, v17
	v_mul_f32_e32 v16, v124, v16
	v_mul_f32_e32 v17, v125, v17
	v_cvt_pk_bf16_f32 v83, v16, v17
	v_lshlrev_b32_e32 v16, 16, v104
	v_and_b32_e32 v17, 0xffff0000, v104
	v_mul_f32_e32 v16, v15, v16
	v_mul_f32_e32 v17, v15, v17
	v_mul_f32_e32 v16, v126, v16
	v_mul_f32_e32 v17, v127, v17
	v_cvt_pk_bf16_f32 v84, v16, v17
	v_lshlrev_b32_e32 v16, 16, v105
	v_and_b32_e32 v17, 0xffff0000, v105
	v_mul_f32_e32 v16, v15, v16
	v_mul_f32_e32 v17, v15, v17
	v_mul_f32_e32 v16, v128, v16
	v_mul_f32_e32 v17, v129, v17
	v_cvt_pk_bf16_f32 v85, v16, v17
	v_lshlrev_b32_e32 v16, 16, v154
	v_and_b32_e32 v17, 0xffff0000, v154
	v_mul_f32_e32 v16, v14, v16
	v_mul_f32_e32 v17, v14, v17
	v_mul_f32_e32 v16, v130, v16
	v_mul_f32_e32 v17, v131, v17
	v_cvt_pk_bf16_f32 v58, v16, v17
	v_lshlrev_b32_e32 v16, 16, v155
	v_and_b32_e32 v17, 0xffff0000, v155
	v_mul_f32_e32 v16, v14, v16
	v_mul_f32_e32 v17, v14, v17
	v_mul_f32_e32 v16, v132, v16
	v_mul_f32_e32 v17, v133, v17
	v_cvt_pk_bf16_f32 v59, v16, v17
	v_lshlrev_b32_e32 v16, 16, v156
	v_and_b32_e32 v17, 0xffff0000, v156
	v_mul_f32_e32 v16, v14, v16
	v_mul_f32_e32 v17, v14, v17
	v_mul_f32_e32 v16, v134, v16
	v_mul_f32_e32 v17, v135, v17
	v_cvt_pk_bf16_f32 v60, v16, v17
	v_lshlrev_b32_e32 v16, 16, v157
	v_and_b32_e32 v17, 0xffff0000, v157
	v_mul_f32_e32 v16, v14, v16
	v_mul_f32_e32 v17, v14, v17
	v_mul_f32_e32 v16, v136, v16
	v_mul_f32_e32 v17, v137, v17
	v_cvt_pk_bf16_f32 v61, v16, v17
	v_lshlrev_b32_e32 v16, 16, v106
	v_and_b32_e32 v17, 0xffff0000, v106
	v_mul_f32_e32 v16, v15, v16
	v_mul_f32_e32 v17, v15, v17
	v_mul_f32_e32 v16, v130, v16
	v_mul_f32_e32 v17, v131, v17
	v_cvt_pk_bf16_f32 v86, v16, v17
	v_lshlrev_b32_e32 v16, 16, v107
	v_and_b32_e32 v17, 0xffff0000, v107
	v_mul_f32_e32 v16, v15, v16
	v_mul_f32_e32 v17, v15, v17
	v_mul_f32_e32 v16, v132, v16
	v_mul_f32_e32 v17, v133, v17
	v_cvt_pk_bf16_f32 v87, v16, v17
	v_lshlrev_b32_e32 v16, 16, v108
	v_and_b32_e32 v17, 0xffff0000, v108
	v_mul_f32_e32 v16, v15, v16
	v_mul_f32_e32 v17, v15, v17
	v_mul_f32_e32 v16, v134, v16
	v_mul_f32_e32 v17, v135, v17
	v_cvt_pk_bf16_f32 v88, v16, v17
	v_lshlrev_b32_e32 v16, 16, v109
	v_and_b32_e32 v17, 0xffff0000, v109
	v_mul_f32_e32 v16, v15, v16
	v_mul_f32_e32 v17, v15, v17
	v_mul_f32_e32 v16, v136, v16
	v_mul_f32_e32 v17, v137, v17
	v_cvt_pk_bf16_f32 v89, v16, v17
	v_lshlrev_b32_e32 v16, 16, v158
	v_and_b32_e32 v17, 0xffff0000, v158
	v_mul_f32_e32 v16, v14, v16
	v_mul_f32_e32 v17, v14, v17
	v_mul_f32_e32 v16, v138, v16
	v_mul_f32_e32 v17, v139, v17
	v_cvt_pk_bf16_f32 v66, v16, v17
	v_lshlrev_b32_e32 v16, 16, v159
	v_and_b32_e32 v17, 0xffff0000, v159
	v_mul_f32_e32 v16, v14, v16
	v_mul_f32_e32 v17, v14, v17
	v_mul_f32_e32 v16, v140, v16
	v_mul_f32_e32 v17, v141, v17
	v_cvt_pk_bf16_f32 v67, v16, v17
	v_lshlrev_b32_e32 v16, 16, v160
	v_and_b32_e32 v17, 0xffff0000, v160
	v_mul_f32_e32 v16, v14, v16
	v_mul_f32_e32 v17, v14, v17
	v_mul_f32_e32 v16, v142, v16
	v_mul_f32_e32 v17, v143, v17
	v_cvt_pk_bf16_f32 v68, v16, v17
	v_lshlrev_b32_e32 v16, 16, v161
	v_and_b32_e32 v17, 0xffff0000, v161
	v_mul_f32_e32 v16, v14, v16
	v_mul_f32_e32 v17, v14, v17
	v_mul_f32_e32 v16, v144, v16
	v_mul_f32_e32 v17, v145, v17
	v_cvt_pk_bf16_f32 v69, v16, v17
	v_lshlrev_b32_e32 v16, 16, v110
	v_and_b32_e32 v17, 0xffff0000, v110
	v_mul_f32_e32 v16, v15, v16
	v_mul_f32_e32 v17, v15, v17
	v_mul_f32_e32 v16, v138, v16
	v_mul_f32_e32 v17, v139, v17
	v_cvt_pk_bf16_f32 v94, v16, v17
	v_lshlrev_b32_e32 v16, 16, v111
	v_and_b32_e32 v17, 0xffff0000, v111
	v_mul_f32_e32 v16, v15, v16
	v_mul_f32_e32 v17, v15, v17
	v_mul_f32_e32 v16, v140, v16
	v_mul_f32_e32 v17, v141, v17
	v_cvt_pk_bf16_f32 v95, v16, v17
	v_lshlrev_b32_e32 v16, 16, v112
	v_and_b32_e32 v17, 0xffff0000, v112
	v_mul_f32_e32 v16, v15, v16
	v_mul_f32_e32 v17, v15, v17
	v_mul_f32_e32 v16, v142, v16
	v_mul_f32_e32 v17, v143, v17
	v_cvt_pk_bf16_f32 v96, v16, v17
	v_lshlrev_b32_e32 v16, 16, v113
	v_and_b32_e32 v17, 0xffff0000, v113
	v_mul_f32_e32 v16, v15, v16
	v_mul_f32_e32 v17, v15, v17
	v_mul_f32_e32 v16, v144, v16
	v_mul_f32_e32 v17, v145, v17
	v_cvt_pk_bf16_f32 v97, v16, v17
	s_bfe_u32 s6, s23, 0x40002
	s_lshl_b32 s7, s6, 1
	v_sub_u32_e64 v2, s7, 4 clamp
	s_and_b32 s10, s26, 48
	v_readfirstlane_b32 s8, v2
	v_sub_u32_e64 v2, s7, 3 clamp
	s_min_u32 s3, s8, 24
	v_readfirstlane_b32 s7, v2
	v_sub_u32_e64 v2, s10, 8 clamp
	v_min_u32_e32 v2, 32, v2
	s_mul_i32 s11, s3, 31
	v_add_u32_e32 v2, s11, v2
	v_add_u32_e32 v2, v2, v173
	v_subrev_u32_e32 v2, s10, v2
	s_mul_i32 s6, s6, 62
	v_subrev_u32_e32 v188, s6, v2
	v_sub_u32_e64 v2, s1, 8 clamp
	s_min_u32 s7, s7, 24
	v_min_u32_e32 v4, 32, v2
	v_or_b32_e32 v2, s1, v192
	s_sub_i32 s6, s7, s3
	v_sub_u32_e64 v2, v2, 8 clamp
	s_add_i32 s6, s6, 15
	s_or_b32 s0, s0, s17
	v_min_u32_e32 v5, 48, v2
	v_or_b32_e32 v2, s13, v192
	s_mul_i32 s42, s0, 0x1d1
	v_readlane_b32 s52, v252, 12
	v_mul_u32_u24_e32 v2, 0x4800, v2
	s_lshl_b32 s8, s3, 5
	s_lshl_b32 s9, s7, 5
	s_lshl_b64 s[0:1], s[42:43], 2
	v_readlane_b32 s64, v252, 24
	v_lshlrev_b32_e32 v2, 1, v2
	v_mov_b32_e32 v3, v195
	v_readlane_b32 s65, v252, 25
	s_add_u32 s0, s64, s0
	v_add_u32_e32 v2, v4, v170
	v_add_u32_e32 v3, 16, v5
	s_addc_u32 s1, s65, s1
	s_lshl_b32 s10, s4, 8
	v_cmp_ge_u32_e32 vcc, v2, v5
	v_cmp_lt_u32_e64 s[4:5], v2, v3
	v_or_b32_e32 v4, 1, v2
	v_readlane_b32 s53, v252, 13
	s_and_b64 s[40:41], vcc, s[4:5]
	v_cmp_ge_u32_e32 vcc, v4, v5
	v_cmp_lt_u32_e64 s[4:5], v4, v3
	v_or_b32_e32 v4, 2, v2
	v_readlane_b32 s54, v252, 14
	v_readlane_b32 s55, v252, 15
	s_and_b64 s[52:53], vcc, s[4:5]
	v_cmp_ge_u32_e32 vcc, v4, v5
	v_cmp_lt_u32_e64 s[4:5], v4, v3
	v_or_b32_e32 v4, 3, v2
	v_readlane_b32 s60, v252, 20
	v_readlane_b32 s61, v252, 21
	s_and_b64 s[54:55], vcc, s[4:5]
	v_cmp_ge_u32_e32 vcc, v4, v5
	v_cmp_lt_u32_e64 s[4:5], v4, v3
	v_or_b32_e32 v4, 4, v2
	v_readlane_b32 s62, v252, 22
	v_readlane_b32 s63, v252, 23
	s_and_b64 s[60:61], vcc, s[4:5]
	v_cmp_ge_u32_e32 vcc, v4, v5
	v_cmp_lt_u32_e64 s[4:5], v4, v3
	v_or_b32_e32 v4, 5, v2
	s_and_b64 s[62:63], vcc, s[4:5]
	v_cmp_ge_u32_e32 vcc, v4, v5
	v_cmp_lt_u32_e64 s[4:5], v4, v3
	v_or_b32_e32 v4, 6, v2
	s_and_b64 s[80:81], vcc, s[4:5]
	v_cmp_ge_u32_e32 vcc, v4, v5
	v_cmp_lt_u32_e64 s[4:5], v4, v3
	v_or_b32_e32 v2, 7, v2
	s_and_b64 s[82:83], vcc, s[4:5]
	v_cmp_ge_u32_e32 vcc, v2, v5
	v_cmp_lt_u32_e64 s[4:5], v2, v3
	s_add_i32 s10, s10, s8
	s_and_b64 s[6:7], vcc, s[4:5]
	s_sub_i32 s4, s10, s9
	v_mov_b32_e32 v175, 0
	s_mov_b32 s70, 0
	v_mov_b32_e32 v253, 0xff800000
	s_movk_i32 s22, 0x1d0
	v_mov_b32_e32 v185, 0xff800000
	v_mov_b32_e32 v203, 0xff800000
	v_mov_b32_e32 v201, 0
	v_mov_b32_e32 v34, 0
	v_mov_b32_e32 v35, v175
	v_mov_b32_e32 v36, v175
	v_mov_b32_e32 v37, v175
	v_mov_b32_e32 v38, 0
	v_mov_b32_e32 v39, v175
	v_mov_b32_e32 v40, v175
	v_mov_b32_e32 v41, v175
	v_mov_b32_e32 v42, 0
	v_mov_b32_e32 v43, v175
	v_mov_b32_e32 v44, v175
	v_mov_b32_e32 v45, v175
	v_mov_b32_e32 v46, 0
	v_mov_b32_e32 v47, v175
	v_mov_b32_e32 v48, v175
	v_mov_b32_e32 v49, v175
	v_mov_b32_e32 v62, 0
	v_mov_b32_e32 v63, v175
	v_mov_b32_e32 v64, v175
	v_mov_b32_e32 v65, v175
	v_mov_b32_e32 v70, 0
	v_mov_b32_e32 v71, v175
	v_mov_b32_e32 v72, v175
	v_mov_b32_e32 v73, v175
	v_mov_b32_e32 v74, 0
	v_mov_b32_e32 v75, v175
	v_mov_b32_e32 v76, v175
	v_mov_b32_e32 v77, v175
	v_mov_b32_e32 v90, 0
	v_mov_b32_e32 v91, v175
	v_mov_b32_e32 v92, v175
	v_mov_b32_e32 v93, v175
	v_mov_b32_e32 v30, 0
	v_mov_b32_e32 v31, v175
	v_mov_b32_e32 v32, v175
	v_mov_b32_e32 v33, v175
	v_mov_b32_e32 v26, 0
	v_mov_b32_e32 v27, v175
	v_mov_b32_e32 v28, v175
	v_mov_b32_e32 v29, v175
	v_mov_b32_e32 v22, 0
	v_mov_b32_e32 v23, v175
	v_mov_b32_e32 v24, v175
	v_mov_b32_e32 v25, v175
	v_mov_b32_e32 v18, 0
	v_mov_b32_e32 v19, v175
	v_mov_b32_e32 v20, v175
	v_mov_b32_e32 v21, v175
	v_mov_b32_e32 v14, 0
	v_mov_b32_e32 v15, v175
	v_mov_b32_e32 v16, v175
	v_mov_b32_e32 v17, v175
	v_mov_b32_e32 v10, 0
	v_mov_b32_e32 v11, v175
	v_mov_b32_e32 v12, v175
	v_mov_b32_e32 v13, v175
	v_mov_b32_e32 v6, 0
	v_mov_b32_e32 v7, v175
	v_mov_b32_e32 v8, v175
	v_mov_b32_e32 v9, v175
	v_mov_b32_e32 v2, 0
	v_mov_b32_e32 v3, v175
	v_mov_b32_e32 v4, v175
	v_mov_b32_e32 v5, v175
	v_readlane_b32 s56, v252, 16
	v_readlane_b32 s57, v252, 17
	v_readlane_b32 s58, v252, 18
	v_readlane_b32 s59, v252, 19
	v_readlane_b32 s66, v252, 26
	v_readlane_b32 s67, v252, 27
